# phase 0: sample-window K / V^T bf16 conversion rewritten per (group, 64-row block) unit with an LDS transpose so V^T is written as 128-byte pieces instead of scattered 2-byte stores (on top of the pha
# speedup vs baseline: 1.0106x; 1.0106x over previous
.LBB0_202:
	s_or_b64 exec, exec, s[4:5]
	s_mov_b32 s3, 0x440000
	v_cmp_gt_i32_e32 vcc, s3, v72
	s_and_saveexec_b64 s[4:5], vcc
	s_cbranch_execz .LBB0_213
	s_add_u32 s6, s30, 0x3ea53000
	s_addc_u32 s7, s31, 0
	s_add_u32 s88, s30, 0x3e1d3000
	s_addc_u32 s89, s31, 0
	s_mov_b64 s[20:21], s[0:1]
	s_load_dwordx2 s[20:21], s[20:21], 0x18
	s_movk_i32 s23, 0x7fff
	v_lshrrev_b32_e32 v1, 6, v0
	s_nop 0
	v_readfirstlane_b32 s82, v1
	s_nop 3
	s_lshl_b32 s83, s2, 3
	s_add_i32 s83, s83, s82
	s_lshr_b32 s84, s16, 7
	v_lshlrev_b32_e32 v6, 2, v146
	v_lshlrev_b32_e32 v7, 1, v146
	v_mov_b32_e32 v5, 0
	s_lshl_b32 s85, s82, 14
	v_mul_u32_u24_e32 v8, 0x88, v146
	v_add_u32_e32 v8, s85, v8
	v_lshrrev_b32_e32 v1, 3, v146
	v_and_b32_e32 v2, 7, v146
	v_mul_u32_u24_e32 v9, 0x88, v1
	v_lshl_add_u32 v9, v2, 4, v9
	v_add_u32_e32 v9, s85, v9
	v_mul_u32_u24_e32 v10, 0x440, v1
	v_lshl_add_u32 v10, v2, 4, v10
	v_mul_u32_u24_e32 v11, 0x440, v146
	v_mov_b32_e32 v12, 0
	v_mov_b32_e32 v13, 0
	s_waitcnt lgkmcnt(0)
	s_bitcmp1_b32 s83, 0
	s_cbranch_scc1 .Lp0_sw_zero
	s_lshr_b32 s83, s83, 1
.Lp0_sw_unit:
	s_cmpk_ge_u32 s83, 0x400
	s_cbranch_scc1 .Lp0_sw_done
	s_lshr_b32 s80, s83, 3
	s_and_b32 s81, s83, 7
	s_lshr_b32 s76, s80, 2
	s_lshl_b32 s76, s76, 20
	s_lshl_b32 s77, s81, 17
	s_add_i32 s76, s76, s77
	s_and_b32 s77, s80, 3
	s_lshl_b32 s77, s77, 8
	s_add_i32 s76, s76, s77
	s_add_u32 s76, s20, s76
	s_addc_u32 s77, s21, 0
	s_mul_i32 s78, s80, 0x220
	s_lshl_b32 s79, s81, 6
	s_add_i32 s78, s78, s79
	s_lshl_b32 s78, s78, 7
	s_add_u32 s78, s88, s78
	s_addc_u32 s79, s89, 0
	s_mul_i32 s94, s80, 0x11000
	s_lshl_b32 s95, s81, 7
	s_add_i32 s94, s94, s95
	s_add_u32 s94, s6, s94
	s_addc_u32 s95, s7, 0
	s_nop 4
	global_load_dword v164, v6, s[76:77]
	global_load_dword v165, v6, s[76:77] offset:1024
	global_load_dword v166, v6, s[76:77] offset:2048
	global_load_dword v167, v6, s[76:77] offset:3072
	s_add_u32 s76, s76, 0x1000
	s_addc_u32 s77, s77, 0
	s_nop 4
	global_load_dword v168, v6, s[76:77]
	global_load_dword v169, v6, s[76:77] offset:1024
	global_load_dword v170, v6, s[76:77] offset:2048
	global_load_dword v171, v6, s[76:77] offset:3072
	s_add_u32 s76, s76, 0x1000
	s_addc_u32 s77, s77, 0
	s_nop 4
	global_load_dword v172, v6, s[76:77]
	global_load_dword v173, v6, s[76:77] offset:1024
	global_load_dword v174, v6, s[76:77] offset:2048
	global_load_dword v175, v6, s[76:77] offset:3072
	s_add_u32 s76, s76, 0x1000
	s_addc_u32 s77, s77, 0
	s_nop 4
	global_load_dword v176, v6, s[76:77]
	global_load_dword v177, v6, s[76:77] offset:1024
	global_load_dword v178, v6, s[76:77] offset:2048
	global_load_dword v179, v6, s[76:77] offset:3072
	s_add_u32 s76, s76, 0x1000
	s_addc_u32 s77, s77, 0
	s_nop 4
	global_load_dword v180, v6, s[76:77]
	global_load_dword v181, v6, s[76:77] offset:1024
	global_load_dword v182, v6, s[76:77] offset:2048
	global_load_dword v183, v6, s[76:77] offset:3072
	s_add_u32 s76, s76, 0x1000
	s_addc_u32 s77, s77, 0
	s_nop 4
	global_load_dword v184, v6, s[76:77]
	global_load_dword v185, v6, s[76:77] offset:1024
	global_load_dword v186, v6, s[76:77] offset:2048
	global_load_dword v187, v6, s[76:77] offset:3072
	s_add_u32 s76, s76, 0x1000
	s_addc_u32 s77, s77, 0
	s_nop 4
	global_load_dword v188, v6, s[76:77]
	global_load_dword v189, v6, s[76:77] offset:1024
	global_load_dword v190, v6, s[76:77] offset:2048
	global_load_dword v191, v6, s[76:77] offset:3072
	s_add_u32 s76, s76, 0x1000
	s_addc_u32 s77, s77, 0
	s_nop 4
	global_load_dword v192, v6, s[76:77]
	global_load_dword v193, v6, s[76:77] offset:1024
	global_load_dword v194, v6, s[76:77] offset:2048
	global_load_dword v195, v6, s[76:77] offset:3072
	s_add_u32 s76, s76, 0x1000
	s_addc_u32 s77, s77, 0
	s_waitcnt vmcnt(30)
	v_bfe_u32 v1, v164, 16, 1
	v_bfe_u32 v2, v165, 16, 1
	v_add3_u32 v164, v164, v1, s23
	v_add3_u32 v165, v165, v2, s23
	s_waitcnt vmcnt(28)
	v_bfe_u32 v1, v166, 16, 1
	v_bfe_u32 v2, v167, 16, 1
	v_add3_u32 v166, v166, v1, s23
	v_add3_u32 v167, v167, v2, s23
	s_waitcnt vmcnt(26)
	v_bfe_u32 v1, v168, 16, 1
	v_bfe_u32 v2, v169, 16, 1
	v_add3_u32 v168, v168, v1, s23
	v_add3_u32 v169, v169, v2, s23
	s_waitcnt vmcnt(24)
	v_bfe_u32 v1, v170, 16, 1
	v_bfe_u32 v2, v171, 16, 1
	v_add3_u32 v170, v170, v1, s23
	v_add3_u32 v171, v171, v2, s23
	s_waitcnt vmcnt(22)
	v_bfe_u32 v1, v172, 16, 1
	v_bfe_u32 v2, v173, 16, 1
	v_add3_u32 v172, v172, v1, s23
	v_add3_u32 v173, v173, v2, s23
	s_waitcnt vmcnt(20)
	v_bfe_u32 v1, v174, 16, 1
	v_bfe_u32 v2, v175, 16, 1
	v_add3_u32 v174, v174, v1, s23
	v_add3_u32 v175, v175, v2, s23
	s_waitcnt vmcnt(18)
	v_bfe_u32 v1, v176, 16, 1
	v_bfe_u32 v2, v177, 16, 1
	v_add3_u32 v176, v176, v1, s23
	v_add3_u32 v177, v177, v2, s23
	s_waitcnt vmcnt(16)
	v_bfe_u32 v1, v178, 16, 1
	v_bfe_u32 v2, v179, 16, 1
	v_add3_u32 v178, v178, v1, s23
	v_add3_u32 v179, v179, v2, s23
	s_waitcnt vmcnt(14)
	v_bfe_u32 v1, v180, 16, 1
	v_bfe_u32 v2, v181, 16, 1
	v_add3_u32 v180, v180, v1, s23
	v_add3_u32 v181, v181, v2, s23
	s_waitcnt vmcnt(12)
	v_bfe_u32 v1, v182, 16, 1
	v_bfe_u32 v2, v183, 16, 1
	v_add3_u32 v182, v182, v1, s23
	v_add3_u32 v183, v183, v2, s23
	s_waitcnt vmcnt(10)
	v_bfe_u32 v1, v184, 16, 1
	v_bfe_u32 v2, v185, 16, 1
	v_add3_u32 v184, v184, v1, s23
	v_add3_u32 v185, v185, v2, s23
	s_waitcnt vmcnt(8)
	v_bfe_u32 v1, v186, 16, 1
	v_bfe_u32 v2, v187, 16, 1
	v_add3_u32 v186, v186, v1, s23
	v_add3_u32 v187, v187, v2, s23
	s_waitcnt vmcnt(6)
	v_bfe_u32 v1, v188, 16, 1
	v_bfe_u32 v2, v189, 16, 1
	v_add3_u32 v188, v188, v1, s23
	v_add3_u32 v189, v189, v2, s23
	s_waitcnt vmcnt(4)
	v_bfe_u32 v1, v190, 16, 1
	v_bfe_u32 v2, v191, 16, 1
	v_add3_u32 v190, v190, v1, s23
	v_add3_u32 v191, v191, v2, s23
	s_waitcnt vmcnt(2)
	v_bfe_u32 v1, v192, 16, 1
	v_bfe_u32 v2, v193, 16, 1
	v_add3_u32 v192, v192, v1, s23
	v_add3_u32 v193, v193, v2, s23
	s_waitcnt vmcnt(0)
	v_bfe_u32 v1, v194, 16, 1
	v_bfe_u32 v2, v195, 16, 1
	v_add3_u32 v194, v194, v1, s23
	v_add3_u32 v195, v195, v2, s23
	global_store_short_d16_hi v7, v164, s[78:79]
	ds_write_b16_d16_hi v8, v165 offset:0
	global_store_short_d16_hi v7, v166, s[78:79] offset:128
	ds_write_b16_d16_hi v8, v167 offset:2
	global_store_short_d16_hi v7, v168, s[78:79] offset:256
	ds_write_b16_d16_hi v8, v169 offset:4
	global_store_short_d16_hi v7, v170, s[78:79] offset:384
	ds_write_b16_d16_hi v8, v171 offset:6
	global_store_short_d16_hi v7, v172, s[78:79] offset:512
	ds_write_b16_d16_hi v8, v173 offset:8
	global_store_short_d16_hi v7, v174, s[78:79] offset:640
	ds_write_b16_d16_hi v8, v175 offset:10
	global_store_short_d16_hi v7, v176, s[78:79] offset:768
	ds_write_b16_d16_hi v8, v177 offset:12
	global_store_short_d16_hi v7, v178, s[78:79] offset:896
	ds_write_b16_d16_hi v8, v179 offset:14
	global_store_short_d16_hi v7, v180, s[78:79] offset:1024
	ds_write_b16_d16_hi v8, v181 offset:16
	global_store_short_d16_hi v7, v182, s[78:79] offset:1152
	ds_write_b16_d16_hi v8, v183 offset:18
	global_store_short_d16_hi v7, v184, s[78:79] offset:1280
	ds_write_b16_d16_hi v8, v185 offset:20
	global_store_short_d16_hi v7, v186, s[78:79] offset:1408
	ds_write_b16_d16_hi v8, v187 offset:22
	global_store_short_d16_hi v7, v188, s[78:79] offset:1536
	ds_write_b16_d16_hi v8, v189 offset:24
	global_store_short_d16_hi v7, v190, s[78:79] offset:1664
	ds_write_b16_d16_hi v8, v191 offset:26
	global_store_short_d16_hi v7, v192, s[78:79] offset:1792
	ds_write_b16_d16_hi v8, v193 offset:28
	global_store_short_d16_hi v7, v194, s[78:79] offset:1920
	ds_write_b16_d16_hi v8, v195 offset:30
	s_add_u32 s78, s78, 0x800
	s_addc_u32 s79, s79, 0
	s_nop 2
	global_load_dword v164, v6, s[76:77]
	global_load_dword v165, v6, s[76:77] offset:1024
	global_load_dword v166, v6, s[76:77] offset:2048
	global_load_dword v167, v6, s[76:77] offset:3072
	s_add_u32 s76, s76, 0x1000
	s_addc_u32 s77, s77, 0
	s_nop 4
	global_load_dword v168, v6, s[76:77]
	global_load_dword v169, v6, s[76:77] offset:1024
	global_load_dword v170, v6, s[76:77] offset:2048
	global_load_dword v171, v6, s[76:77] offset:3072
	s_add_u32 s76, s76, 0x1000
	s_addc_u32 s77, s77, 0
	s_nop 4
	global_load_dword v172, v6, s[76:77]
	global_load_dword v173, v6, s[76:77] offset:1024
	global_load_dword v174, v6, s[76:77] offset:2048
	global_load_dword v175, v6, s[76:77] offset:3072
	s_add_u32 s76, s76, 0x1000
	s_addc_u32 s77, s77, 0
	s_nop 4
	global_load_dword v176, v6, s[76:77]
	global_load_dword v177, v6, s[76:77] offset:1024
	global_load_dword v178, v6, s[76:77] offset:2048
	global_load_dword v179, v6, s[76:77] offset:3072
	s_add_u32 s76, s76, 0x1000
	s_addc_u32 s77, s77, 0
	s_nop 4
	global_load_dword v180, v6, s[76:77]
	global_load_dword v181, v6, s[76:77] offset:1024
	global_load_dword v182, v6, s[76:77] offset:2048
	global_load_dword v183, v6, s[76:77] offset:3072
	s_add_u32 s76, s76, 0x1000
	s_addc_u32 s77, s77, 0
	s_nop 4
	global_load_dword v184, v6, s[76:77]
	global_load_dword v185, v6, s[76:77] offset:1024
	global_load_dword v186, v6, s[76:77] offset:2048
	global_load_dword v187, v6, s[76:77] offset:3072
	s_add_u32 s76, s76, 0x1000
	s_addc_u32 s77, s77, 0
	s_nop 4
	global_load_dword v188, v6, s[76:77]
	global_load_dword v189, v6, s[76:77] offset:1024
	global_load_dword v190, v6, s[76:77] offset:2048
	global_load_dword v191, v6, s[76:77] offset:3072
	s_add_u32 s76, s76, 0x1000
	s_addc_u32 s77, s77, 0
	s_nop 4
	global_load_dword v192, v6, s[76:77]
	global_load_dword v193, v6, s[76:77] offset:1024
	global_load_dword v194, v6, s[76:77] offset:2048
	global_load_dword v195, v6, s[76:77] offset:3072
	s_add_u32 s76, s76, 0x1000
	s_addc_u32 s77, s77, 0
	s_waitcnt vmcnt(30)
	v_bfe_u32 v1, v164, 16, 1
	v_bfe_u32 v2, v165, 16, 1
	v_add3_u32 v164, v164, v1, s23
	v_add3_u32 v165, v165, v2, s23
	s_waitcnt vmcnt(28)
	v_bfe_u32 v1, v166, 16, 1
	v_bfe_u32 v2, v167, 16, 1
	v_add3_u32 v166, v166, v1, s23
	v_add3_u32 v167, v167, v2, s23
	s_waitcnt vmcnt(26)
	v_bfe_u32 v1, v168, 16, 1
	v_bfe_u32 v2, v169, 16, 1
	v_add3_u32 v168, v168, v1, s23
	v_add3_u32 v169, v169, v2, s23
	s_waitcnt vmcnt(24)
	v_bfe_u32 v1, v170, 16, 1
	v_bfe_u32 v2, v171, 16, 1
	v_add3_u32 v170, v170, v1, s23
	v_add3_u32 v171, v171, v2, s23
	s_waitcnt vmcnt(22)
	v_bfe_u32 v1, v172, 16, 1
	v_bfe_u32 v2, v173, 16, 1
	v_add3_u32 v172, v172, v1, s23
	v_add3_u32 v173, v173, v2, s23
	s_waitcnt vmcnt(20)
	v_bfe_u32 v1, v174, 16, 1
	v_bfe_u32 v2, v175, 16, 1
	v_add3_u32 v174, v174, v1, s23
	v_add3_u32 v175, v175, v2, s23
	s_waitcnt vmcnt(18)
	v_bfe_u32 v1, v176, 16, 1
	v_bfe_u32 v2, v177, 16, 1
	v_add3_u32 v176, v176, v1, s23
	v_add3_u32 v177, v177, v2, s23
	s_waitcnt vmcnt(16)
	v_bfe_u32 v1, v178, 16, 1
	v_bfe_u32 v2, v179, 16, 1
	v_add3_u32 v178, v178, v1, s23
	v_add3_u32 v179, v179, v2, s23
	s_waitcnt vmcnt(14)
	v_bfe_u32 v1, v180, 16, 1
	v_bfe_u32 v2, v181, 16, 1
	v_add3_u32 v180, v180, v1, s23
	v_add3_u32 v181, v181, v2, s23
	s_waitcnt vmcnt(12)
	v_bfe_u32 v1, v182, 16, 1
	v_bfe_u32 v2, v183, 16, 1
	v_add3_u32 v182, v182, v1, s23
	v_add3_u32 v183, v183, v2, s23
	s_waitcnt vmcnt(10)
	v_bfe_u32 v1, v184, 16, 1
	v_bfe_u32 v2, v185, 16, 1
	v_add3_u32 v184, v184, v1, s23
	v_add3_u32 v185, v185, v2, s23
	s_waitcnt vmcnt(8)
	v_bfe_u32 v1, v186, 16, 1
	v_bfe_u32 v2, v187, 16, 1
	v_add3_u32 v186, v186, v1, s23
	v_add3_u32 v187, v187, v2, s23
	s_waitcnt vmcnt(6)
	v_bfe_u32 v1, v188, 16, 1
	v_bfe_u32 v2, v189, 16, 1
	v_add3_u32 v188, v188, v1, s23
	v_add3_u32 v189, v189, v2, s23
	s_waitcnt vmcnt(4)
	v_bfe_u32 v1, v190, 16, 1
	v_bfe_u32 v2, v191, 16, 1
	v_add3_u32 v190, v190, v1, s23
	v_add3_u32 v191, v191, v2, s23
	s_waitcnt vmcnt(2)
	v_bfe_u32 v1, v192, 16, 1
	v_bfe_u32 v2, v193, 16, 1
	v_add3_u32 v192, v192, v1, s23
	v_add3_u32 v193, v193, v2, s23
	s_waitcnt vmcnt(0)
	v_bfe_u32 v1, v194, 16, 1
	v_bfe_u32 v2, v195, 16, 1
	v_add3_u32 v194, v194, v1, s23
	v_add3_u32 v195, v195, v2, s23
	global_store_short_d16_hi v7, v164, s[78:79]
	ds_write_b16_d16_hi v8, v165 offset:32
	global_store_short_d16_hi v7, v166, s[78:79] offset:128
	ds_write_b16_d16_hi v8, v167 offset:34
	global_store_short_d16_hi v7, v168, s[78:79] offset:256
	ds_write_b16_d16_hi v8, v169 offset:36
	global_store_short_d16_hi v7, v170, s[78:79] offset:384
	ds_write_b16_d16_hi v8, v171 offset:38
	global_store_short_d16_hi v7, v172, s[78:79] offset:512
	ds_write_b16_d16_hi v8, v173 offset:40
	global_store_short_d16_hi v7, v174, s[78:79] offset:640
	ds_write_b16_d16_hi v8, v175 offset:42
	global_store_short_d16_hi v7, v176, s[78:79] offset:768
	ds_write_b16_d16_hi v8, v177 offset:44
	global_store_short_d16_hi v7, v178, s[78:79] offset:896
	ds_write_b16_d16_hi v8, v179 offset:46
	global_store_short_d16_hi v7, v180, s[78:79] offset:1024
	ds_write_b16_d16_hi v8, v181 offset:48
	global_store_short_d16_hi v7, v182, s[78:79] offset:1152
	ds_write_b16_d16_hi v8, v183 offset:50
	global_store_short_d16_hi v7, v184, s[78:79] offset:1280
	ds_write_b16_d16_hi v8, v185 offset:52
	global_store_short_d16_hi v7, v186, s[78:79] offset:1408
	ds_write_b16_d16_hi v8, v187 offset:54
	global_store_short_d16_hi v7, v188, s[78:79] offset:1536
	ds_write_b16_d16_hi v8, v189 offset:56
	global_store_short_d16_hi v7, v190, s[78:79] offset:1664
	ds_write_b16_d16_hi v8, v191 offset:58
	global_store_short_d16_hi v7, v192, s[78:79] offset:1792
	ds_write_b16_d16_hi v8, v193 offset:60
	global_store_short_d16_hi v7, v194, s[78:79] offset:1920
	ds_write_b16_d16_hi v8, v195 offset:62
	s_add_u32 s78, s78, 0x800
	s_addc_u32 s79, s79, 0
	s_nop 2
	global_load_dword v164, v6, s[76:77]
	global_load_dword v165, v6, s[76:77] offset:1024
	global_load_dword v166, v6, s[76:77] offset:2048
	global_load_dword v167, v6, s[76:77] offset:3072
	s_add_u32 s76, s76, 0x1000
	s_addc_u32 s77, s77, 0
	s_nop 4
	global_load_dword v168, v6, s[76:77]
	global_load_dword v169, v6, s[76:77] offset:1024
	global_load_dword v170, v6, s[76:77] offset:2048
	global_load_dword v171, v6, s[76:77] offset:3072
	s_add_u32 s76, s76, 0x1000
	s_addc_u32 s77, s77, 0
	s_nop 4
	global_load_dword v172, v6, s[76:77]
	global_load_dword v173, v6, s[76:77] offset:1024
	global_load_dword v174, v6, s[76:77] offset:2048
	global_load_dword v175, v6, s[76:77] offset:3072
	s_add_u32 s76, s76, 0x1000
	s_addc_u32 s77, s77, 0
	s_nop 4
	global_load_dword v176, v6, s[76:77]
	global_load_dword v177, v6, s[76:77] offset:1024
	global_load_dword v178, v6, s[76:77] offset:2048
	global_load_dword v179, v6, s[76:77] offset:3072
	s_add_u32 s76, s76, 0x1000
	s_addc_u32 s77, s77, 0
	s_nop 4
	global_load_dword v180, v6, s[76:77]
	global_load_dword v181, v6, s[76:77] offset:1024
	global_load_dword v182, v6, s[76:77] offset:2048
	global_load_dword v183, v6, s[76:77] offset:3072
	s_add_u32 s76, s76, 0x1000
	s_addc_u32 s77, s77, 0
	s_nop 4
	global_load_dword v184, v6, s[76:77]
	global_load_dword v185, v6, s[76:77] offset:1024
	global_load_dword v186, v6, s[76:77] offset:2048
	global_load_dword v187, v6, s[76:77] offset:3072
	s_add_u32 s76, s76, 0x1000
	s_addc_u32 s77, s77, 0
	s_nop 4
	global_load_dword v188, v6, s[76:77]
	global_load_dword v189, v6, s[76:77] offset:1024
	global_load_dword v190, v6, s[76:77] offset:2048
	global_load_dword v191, v6, s[76:77] offset:3072
	s_add_u32 s76, s76, 0x1000
	s_addc_u32 s77, s77, 0
	s_nop 4
	global_load_dword v192, v6, s[76:77]
	global_load_dword v193, v6, s[76:77] offset:1024
	global_load_dword v194, v6, s[76:77] offset:2048
	global_load_dword v195, v6, s[76:77] offset:3072
	s_add_u32 s76, s76, 0x1000
	s_addc_u32 s77, s77, 0
	s_waitcnt vmcnt(30)
	v_bfe_u32 v1, v164, 16, 1
	v_bfe_u32 v2, v165, 16, 1
	v_add3_u32 v164, v164, v1, s23
	v_add3_u32 v165, v165, v2, s23
	s_waitcnt vmcnt(28)
	v_bfe_u32 v1, v166, 16, 1
	v_bfe_u32 v2, v167, 16, 1
	v_add3_u32 v166, v166, v1, s23
	v_add3_u32 v167, v167, v2, s23
	s_waitcnt vmcnt(26)
	v_bfe_u32 v1, v168, 16, 1
	v_bfe_u32 v2, v169, 16, 1
	v_add3_u32 v168, v168, v1, s23
	v_add3_u32 v169, v169, v2, s23
	s_waitcnt vmcnt(24)
	v_bfe_u32 v1, v170, 16, 1
	v_bfe_u32 v2, v171, 16, 1
	v_add3_u32 v170, v170, v1, s23
	v_add3_u32 v171, v171, v2, s23
	s_waitcnt vmcnt(22)
	v_bfe_u32 v1, v172, 16, 1
	v_bfe_u32 v2, v173, 16, 1
	v_add3_u32 v172, v172, v1, s23
	v_add3_u32 v173, v173, v2, s23
	s_waitcnt vmcnt(20)
	v_bfe_u32 v1, v174, 16, 1
	v_bfe_u32 v2, v175, 16, 1
	v_add3_u32 v174, v174, v1, s23
	v_add3_u32 v175, v175, v2, s23
	s_waitcnt vmcnt(18)
	v_bfe_u32 v1, v176, 16, 1
	v_bfe_u32 v2, v177, 16, 1
	v_add3_u32 v176, v176, v1, s23
	v_add3_u32 v177, v177, v2, s23
	s_waitcnt vmcnt(16)
	v_bfe_u32 v1, v178, 16, 1
	v_bfe_u32 v2, v179, 16, 1
	v_add3_u32 v178, v178, v1, s23
	v_add3_u32 v179, v179, v2, s23
	s_waitcnt vmcnt(14)
	v_bfe_u32 v1, v180, 16, 1
	v_bfe_u32 v2, v181, 16, 1
	v_add3_u32 v180, v180, v1, s23
	v_add3_u32 v181, v181, v2, s23
	s_waitcnt vmcnt(12)
	v_bfe_u32 v1, v182, 16, 1
	v_bfe_u32 v2, v183, 16, 1
	v_add3_u32 v182, v182, v1, s23
	v_add3_u32 v183, v183, v2, s23
	s_waitcnt vmcnt(10)
	v_bfe_u32 v1, v184, 16, 1
	v_bfe_u32 v2, v185, 16, 1
	v_add3_u32 v184, v184, v1, s23
	v_add3_u32 v185, v185, v2, s23
	s_waitcnt vmcnt(8)
	v_bfe_u32 v1, v186, 16, 1
	v_bfe_u32 v2, v187, 16, 1
	v_add3_u32 v186, v186, v1, s23
	v_add3_u32 v187, v187, v2, s23
	s_waitcnt vmcnt(6)
	v_bfe_u32 v1, v188, 16, 1
	v_bfe_u32 v2, v189, 16, 1
	v_add3_u32 v188, v188, v1, s23
	v_add3_u32 v189, v189, v2, s23
	s_waitcnt vmcnt(4)
	v_bfe_u32 v1, v190, 16, 1
	v_bfe_u32 v2, v191, 16, 1
	v_add3_u32 v190, v190, v1, s23
	v_add3_u32 v191, v191, v2, s23
	s_waitcnt vmcnt(2)
	v_bfe_u32 v1, v192, 16, 1
	v_bfe_u32 v2, v193, 16, 1
	v_add3_u32 v192, v192, v1, s23
	v_add3_u32 v193, v193, v2, s23
	s_waitcnt vmcnt(0)
	v_bfe_u32 v1, v194, 16, 1
	v_bfe_u32 v2, v195, 16, 1
	v_add3_u32 v194, v194, v1, s23
	v_add3_u32 v195, v195, v2, s23
	global_store_short_d16_hi v7, v164, s[78:79]
	ds_write_b16_d16_hi v8, v165 offset:64
	global_store_short_d16_hi v7, v166, s[78:79] offset:128
	ds_write_b16_d16_hi v8, v167 offset:66
	global_store_short_d16_hi v7, v168, s[78:79] offset:256
	ds_write_b16_d16_hi v8, v169 offset:68
	global_store_short_d16_hi v7, v170, s[78:79] offset:384
	ds_write_b16_d16_hi v8, v171 offset:70
	global_store_short_d16_hi v7, v172, s[78:79] offset:512
	ds_write_b16_d16_hi v8, v173 offset:72
	global_store_short_d16_hi v7, v174, s[78:79] offset:640
	ds_write_b16_d16_hi v8, v175 offset:74
	global_store_short_d16_hi v7, v176, s[78:79] offset:768
	ds_write_b16_d16_hi v8, v177 offset:76
	global_store_short_d16_hi v7, v178, s[78:79] offset:896
	ds_write_b16_d16_hi v8, v179 offset:78
	global_store_short_d16_hi v7, v180, s[78:79] offset:1024
	ds_write_b16_d16_hi v8, v181 offset:80
	global_store_short_d16_hi v7, v182, s[78:79] offset:1152
	ds_write_b16_d16_hi v8, v183 offset:82
	global_store_short_d16_hi v7, v184, s[78:79] offset:1280
	ds_write_b16_d16_hi v8, v185 offset:84
	global_store_short_d16_hi v7, v186, s[78:79] offset:1408
	ds_write_b16_d16_hi v8, v187 offset:86
	global_store_short_d16_hi v7, v188, s[78:79] offset:1536
	ds_write_b16_d16_hi v8, v189 offset:88
	global_store_short_d16_hi v7, v190, s[78:79] offset:1664
	ds_write_b16_d16_hi v8, v191 offset:90
	global_store_short_d16_hi v7, v192, s[78:79] offset:1792
	ds_write_b16_d16_hi v8, v193 offset:92
	global_store_short_d16_hi v7, v194, s[78:79] offset:1920
	ds_write_b16_d16_hi v8, v195 offset:94
	s_add_u32 s78, s78, 0x800
	s_addc_u32 s79, s79, 0
	s_nop 2
	global_load_dword v164, v6, s[76:77]
	global_load_dword v165, v6, s[76:77] offset:1024
	global_load_dword v166, v6, s[76:77] offset:2048
	global_load_dword v167, v6, s[76:77] offset:3072
	s_add_u32 s76, s76, 0x1000
	s_addc_u32 s77, s77, 0
	s_nop 4
	global_load_dword v168, v6, s[76:77]
	global_load_dword v169, v6, s[76:77] offset:1024
	global_load_dword v170, v6, s[76:77] offset:2048
	global_load_dword v171, v6, s[76:77] offset:3072
	s_add_u32 s76, s76, 0x1000
	s_addc_u32 s77, s77, 0
	s_nop 4
	global_load_dword v172, v6, s[76:77]
	global_load_dword v173, v6, s[76:77] offset:1024
	global_load_dword v174, v6, s[76:77] offset:2048
	global_load_dword v175, v6, s[76:77] offset:3072
	s_add_u32 s76, s76, 0x1000
	s_addc_u32 s77, s77, 0
	s_nop 4
	global_load_dword v176, v6, s[76:77]
	global_load_dword v177, v6, s[76:77] offset:1024
	global_load_dword v178, v6, s[76:77] offset:2048
	global_load_dword v179, v6, s[76:77] offset:3072
	s_add_u32 s76, s76, 0x1000
	s_addc_u32 s77, s77, 0
	s_nop 4
	global_load_dword v180, v6, s[76:77]
	global_load_dword v181, v6, s[76:77] offset:1024
	global_load_dword v182, v6, s[76:77] offset:2048
	global_load_dword v183, v6, s[76:77] offset:3072
	s_add_u32 s76, s76, 0x1000
	s_addc_u32 s77, s77, 0
	s_nop 4
	global_load_dword v184, v6, s[76:77]
	global_load_dword v185, v6, s[76:77] offset:1024
	global_load_dword v186, v6, s[76:77] offset:2048
	global_load_dword v187, v6, s[76:77] offset:3072
	s_add_u32 s76, s76, 0x1000
	s_addc_u32 s77, s77, 0
	s_nop 4
	global_load_dword v188, v6, s[76:77]
	global_load_dword v189, v6, s[76:77] offset:1024
	global_load_dword v190, v6, s[76:77] offset:2048
	global_load_dword v191, v6, s[76:77] offset:3072
	s_add_u32 s76, s76, 0x1000
	s_addc_u32 s77, s77, 0
	s_nop 4
	global_load_dword v192, v6, s[76:77]
	global_load_dword v193, v6, s[76:77] offset:1024
	global_load_dword v194, v6, s[76:77] offset:2048
	global_load_dword v195, v6, s[76:77] offset:3072
	s_add_u32 s76, s76, 0x1000
	s_addc_u32 s77, s77, 0
	s_waitcnt vmcnt(30)
	v_bfe_u32 v1, v164, 16, 1
	v_bfe_u32 v2, v165, 16, 1
	v_add3_u32 v164, v164, v1, s23
	v_add3_u32 v165, v165, v2, s23
	s_waitcnt vmcnt(28)
	v_bfe_u32 v1, v166, 16, 1
	v_bfe_u32 v2, v167, 16, 1
	v_add3_u32 v166, v166, v1, s23
	v_add3_u32 v167, v167, v2, s23
	s_waitcnt vmcnt(26)
	v_bfe_u32 v1, v168, 16, 1
	v_bfe_u32 v2, v169, 16, 1
	v_add3_u32 v168, v168, v1, s23
	v_add3_u32 v169, v169, v2, s23
	s_waitcnt vmcnt(24)
	v_bfe_u32 v1, v170, 16, 1
	v_bfe_u32 v2, v171, 16, 1
	v_add3_u32 v170, v170, v1, s23
	v_add3_u32 v171, v171, v2, s23
	s_waitcnt vmcnt(22)
	v_bfe_u32 v1, v172, 16, 1
	v_bfe_u32 v2, v173, 16, 1
	v_add3_u32 v172, v172, v1, s23
	v_add3_u32 v173, v173, v2, s23
	s_waitcnt vmcnt(20)
	v_bfe_u32 v1, v174, 16, 1
	v_bfe_u32 v2, v175, 16, 1
	v_add3_u32 v174, v174, v1, s23
	v_add3_u32 v175, v175, v2, s23
	s_waitcnt vmcnt(18)
	v_bfe_u32 v1, v176, 16, 1
	v_bfe_u32 v2, v177, 16, 1
	v_add3_u32 v176, v176, v1, s23
	v_add3_u32 v177, v177, v2, s23
	s_waitcnt vmcnt(16)
	v_bfe_u32 v1, v178, 16, 1
	v_bfe_u32 v2, v179, 16, 1
	v_add3_u32 v178, v178, v1, s23
	v_add3_u32 v179, v179, v2, s23
	s_waitcnt vmcnt(14)
	v_bfe_u32 v1, v180, 16, 1
	v_bfe_u32 v2, v181, 16, 1
	v_add3_u32 v180, v180, v1, s23
	v_add3_u32 v181, v181, v2, s23
	s_waitcnt vmcnt(12)
	v_bfe_u32 v1, v182, 16, 1
	v_bfe_u32 v2, v183, 16, 1
	v_add3_u32 v182, v182, v1, s23
	v_add3_u32 v183, v183, v2, s23
	s_waitcnt vmcnt(10)
	v_bfe_u32 v1, v184, 16, 1
	v_bfe_u32 v2, v185, 16, 1
	v_add3_u32 v184, v184, v1, s23
	v_add3_u32 v185, v185, v2, s23
	s_waitcnt vmcnt(8)
	v_bfe_u32 v1, v186, 16, 1
	v_bfe_u32 v2, v187, 16, 1
	v_add3_u32 v186, v186, v1, s23
	v_add3_u32 v187, v187, v2, s23
	s_waitcnt vmcnt(6)
	v_bfe_u32 v1, v188, 16, 1
	v_bfe_u32 v2, v189, 16, 1
	v_add3_u32 v188, v188, v1, s23
	v_add3_u32 v189, v189, v2, s23
	s_waitcnt vmcnt(4)
	v_bfe_u32 v1, v190, 16, 1
	v_bfe_u32 v2, v191, 16, 1
	v_add3_u32 v190, v190, v1, s23
	v_add3_u32 v191, v191, v2, s23
	s_waitcnt vmcnt(2)
	v_bfe_u32 v1, v192, 16, 1
	v_bfe_u32 v2, v193, 16, 1
	v_add3_u32 v192, v192, v1, s23
	v_add3_u32 v193, v193, v2, s23
	s_waitcnt vmcnt(0)
	v_bfe_u32 v1, v194, 16, 1
	v_bfe_u32 v2, v195, 16, 1
	v_add3_u32 v194, v194, v1, s23
	v_add3_u32 v195, v195, v2, s23
	global_store_short_d16_hi v7, v164, s[78:79]
	ds_write_b16_d16_hi v8, v165 offset:96
	global_store_short_d16_hi v7, v166, s[78:79] offset:128
	ds_write_b16_d16_hi v8, v167 offset:98
	global_store_short_d16_hi v7, v168, s[78:79] offset:256
	ds_write_b16_d16_hi v8, v169 offset:100
	global_store_short_d16_hi v7, v170, s[78:79] offset:384
	ds_write_b16_d16_hi v8, v171 offset:102
	global_store_short_d16_hi v7, v172, s[78:79] offset:512
	ds_write_b16_d16_hi v8, v173 offset:104
	global_store_short_d16_hi v7, v174, s[78:79] offset:640
	ds_write_b16_d16_hi v8, v175 offset:106
	global_store_short_d16_hi v7, v176, s[78:79] offset:768
	ds_write_b16_d16_hi v8, v177 offset:108
	global_store_short_d16_hi v7, v178, s[78:79] offset:896
	ds_write_b16_d16_hi v8, v179 offset:110
	global_store_short_d16_hi v7, v180, s[78:79] offset:1024
	ds_write_b16_d16_hi v8, v181 offset:112
	global_store_short_d16_hi v7, v182, s[78:79] offset:1152
	ds_write_b16_d16_hi v8, v183 offset:114
	global_store_short_d16_hi v7, v184, s[78:79] offset:1280
	ds_write_b16_d16_hi v8, v185 offset:116
	global_store_short_d16_hi v7, v186, s[78:79] offset:1408
	ds_write_b16_d16_hi v8, v187 offset:118
	global_store_short_d16_hi v7, v188, s[78:79] offset:1536
	ds_write_b16_d16_hi v8, v189 offset:120
	global_store_short_d16_hi v7, v190, s[78:79] offset:1664
	ds_write_b16_d16_hi v8, v191 offset:122
	global_store_short_d16_hi v7, v192, s[78:79] offset:1792
	ds_write_b16_d16_hi v8, v193 offset:124
	global_store_short_d16_hi v7, v194, s[78:79] offset:1920
	ds_write_b16_d16_hi v8, v195 offset:126
	s_add_u32 s78, s78, 0x800
	s_addc_u32 s79, s79, 0
	s_nop 2
	s_waitcnt lgkmcnt(0)
	ds_read_b64 v[164:165], v9 offset:0
	ds_read_b64 v[166:167], v9 offset:8
	ds_read_b64 v[168:169], v9 offset:1088
	ds_read_b64 v[170:171], v9 offset:1096
	ds_read_b64 v[172:173], v9 offset:2176
	ds_read_b64 v[174:175], v9 offset:2184
	ds_read_b64 v[176:177], v9 offset:3264
	ds_read_b64 v[178:179], v9 offset:3272
	ds_read_b64 v[180:181], v9 offset:4352
	ds_read_b64 v[182:183], v9 offset:4360
	ds_read_b64 v[184:185], v9 offset:5440
	ds_read_b64 v[186:187], v9 offset:5448
	ds_read_b64 v[188:189], v9 offset:6528
	ds_read_b64 v[190:191], v9 offset:6536
	ds_read_b64 v[192:193], v9 offset:7616
	ds_read_b64 v[194:195], v9 offset:7624
	s_waitcnt lgkmcnt(14)
	global_store_dwordx4 v10, v[164:167], s[94:95]
	s_add_u32 s94, s94, 0x2200
	s_addc_u32 s95, s95, 0
	s_nop 4
	s_waitcnt lgkmcnt(12)
	global_store_dwordx4 v10, v[168:171], s[94:95]
	s_add_u32 s94, s94, 0x2200
	s_addc_u32 s95, s95, 0
	s_nop 4
	s_waitcnt lgkmcnt(10)
	global_store_dwordx4 v10, v[172:175], s[94:95]
	s_add_u32 s94, s94, 0x2200
	s_addc_u32 s95, s95, 0
	s_nop 4
	s_waitcnt lgkmcnt(8)
	global_store_dwordx4 v10, v[176:179], s[94:95]
	s_add_u32 s94, s94, 0x2200
	s_addc_u32 s95, s95, 0
	s_nop 4
	s_waitcnt lgkmcnt(6)
	global_store_dwordx4 v10, v[180:183], s[94:95]
	s_add_u32 s94, s94, 0x2200
	s_addc_u32 s95, s95, 0
	s_nop 4
	s_waitcnt lgkmcnt(4)
	global_store_dwordx4 v10, v[184:187], s[94:95]
	s_add_u32 s94, s94, 0x2200
	s_addc_u32 s95, s95, 0
	s_nop 4
	s_waitcnt lgkmcnt(2)
	global_store_dwordx4 v10, v[188:191], s[94:95]
	s_add_u32 s94, s94, 0x2200
	s_addc_u32 s95, s95, 0
	s_nop 4
	s_waitcnt lgkmcnt(0)
	global_store_dwordx4 v10, v[192:195], s[94:95]
	s_add_u32 s94, s94, 0x2200
	s_addc_u32 s95, s95, 0
	s_nop 4
	s_add_i32 s83, s83, s84
	s_branch .Lp0_sw_unit
.Lp0_sw_zero:
	s_lshr_b32 s83, s83, 1
.Lp0_sw_zunit:
	s_cmpk_ge_u32 s83, 0x80
	s_cbranch_scc1 .Lp0_sw_done
	s_mul_i32 s78, s83, 0x220
	s_add_i32 s78, s78, 0x204
	s_lshl_b32 s78, s78, 7
	s_add_u32 s78, s88, s78
	s_addc_u32 s79, s89, 0
	s_mul_i32 s94, s83, 0x11000
	s_add_i32 s94, s94, 0x408
	s_add_u32 s94, s6, s94
	s_addc_u32 s95, s7, 0
	s_nop 4
	global_store_short v7, v5, s[78:79]
	global_store_short v7, v5, s[78:79] offset:128
	global_store_short v7, v5, s[78:79] offset:256
	global_store_short v7, v5, s[78:79] offset:384
	global_store_short v7, v5, s[78:79] offset:512
	global_store_short v7, v5, s[78:79] offset:640
	global_store_short v7, v5, s[78:79] offset:768
	global_store_short v7, v5, s[78:79] offset:896
	global_store_short v7, v5, s[78:79] offset:1024
	global_store_short v7, v5, s[78:79] offset:1152
	global_store_short v7, v5, s[78:79] offset:1280
	global_store_short v7, v5, s[78:79] offset:1408
	global_store_short v7, v5, s[78:79] offset:1536
	global_store_short v7, v5, s[78:79] offset:1664
	global_store_short v7, v5, s[78:79] offset:1792
	global_store_short v7, v5, s[78:79] offset:1920
	global_store_short v7, v5, s[78:79] offset:2048
	global_store_short v7, v5, s[78:79] offset:2176
	global_store_short v7, v5, s[78:79] offset:2304
	global_store_short v7, v5, s[78:79] offset:2432
	global_store_short v7, v5, s[78:79] offset:2560
	global_store_short v7, v5, s[78:79] offset:2688
	global_store_short v7, v5, s[78:79] offset:2816
	global_store_short v7, v5, s[78:79] offset:2944
	global_store_short v7, v5, s[78:79] offset:3072
	global_store_short v7, v5, s[78:79] offset:3200
	global_store_short v7, v5, s[78:79] offset:3328
	global_store_short v7, v5, s[78:79] offset:3456
	global_store_dwordx2 v11, v[12:13], s[94:95]
	global_store_dwordx2 v11, v[12:13], s[94:95] offset:8
	global_store_dwordx2 v11, v[12:13], s[94:95] offset:16
	global_store_dwordx2 v11, v[12:13], s[94:95] offset:24
	global_store_dwordx2 v11, v[12:13], s[94:95] offset:32
	global_store_dwordx2 v11, v[12:13], s[94:95] offset:40
	global_store_dwordx2 v11, v[12:13], s[94:95] offset:48
	s_add_i32 s83, s83, s84
	s_branch .Lp0_sw_zunit
.Lp0_sw_done:
	s_waitcnt vmcnt(0) lgkmcnt(0)
